# tile epilogues: waves 4-7 start their epilogue 192 clocks late (s_sleep 3) so SIMD-partner waits stop coinciding
# speedup vs baseline: 1.0121x; 1.0121x over previous
; #define PG8_BAR __builtin_amdgcn_s_barrier()
; template <class Epi, class Sched, bool ALIGN_EPI = false, bool SP2 = false>
; __device__ __forceinline__ void gemm_phase(PG8_LAS unsigned char* lds, const Gemm g, const Sched& S, const Epi& E) {
;     ...
;         if constexpr (ALIGN_EPI) { if (wr == 0) PG8_BAR; }
;         if constexpr (!Epi::AFTER_DRAIN) { E(acc, cur, wr, wc, fr, fq); S.done(cur); }
.LBB0_194:
	s_cmp_lg_u64 s[16:17], 0
	s_cbranch_scc1 .Lskew_0
	s_sleep 3

; #define PG8_BAR __builtin_amdgcn_s_barrier()
; template <class Epi, class Sched, bool ALIGN_EPI = false, bool SP2 = false>
; __device__ __forceinline__ void gemm_phase(PG8_LAS unsigned char* lds, const Gemm g, const Sched& S, const Epi& E) {
;     ...
;         if constexpr (ALIGN_EPI) { if (wr == 0) PG8_BAR; }
;         if constexpr (!Epi::AFTER_DRAIN) { E(acc, cur, wr, wc, fr, fq); S.done(cur); }
.LBB0_272:
	s_cmp_lg_u64 s[44:45], 0
	s_cbranch_scc1 .Lskew_1
	s_sleep 3

; #define PG8_BAR __builtin_amdgcn_s_barrier()
; template <class Epi, class Sched, bool ALIGN_EPI = false, bool SP2 = false>
; __device__ __forceinline__ void gemm_phase(PG8_LAS unsigned char* lds, const Gemm g, const Sched& S, const Epi& E) {
;     ...
;         if constexpr (ALIGN_EPI) { if (wr == 0) PG8_BAR; }
;         if constexpr (!Epi::AFTER_DRAIN) { E(acc, cur, wr, wc, fr, fq); S.done(cur); }
.LBB0_420:
	s_cmp_lg_u64 s[10:11], 0
	s_cbranch_scc1 .Lskew_2
	s_sleep 3

; #define PG8_BAR __builtin_amdgcn_s_barrier()
; template <class Epi, class Sched, bool ALIGN_EPI = false, bool SP2 = false>
; __device__ __forceinline__ void gemm_phase(PG8_LAS unsigned char* lds, const Gemm g, const Sched& S, const Epi& E) {
;     ...
;         if constexpr (ALIGN_EPI) { if (wr == 0) PG8_BAR; }
;         if constexpr (!Epi::AFTER_DRAIN) { E(acc, cur, wr, wc, fr, fq); S.done(cur); }
.LBB0_876:
	s_cmp_lg_u64 s[42:43], 0
	s_cbranch_scc1 .Lskew_6
	s_sleep 3

; #define PG8_BAR __builtin_amdgcn_s_barrier()
; template <class Epi, class Sched, bool ALIGN_EPI = false, bool SP2 = false>
; __device__ __forceinline__ void gemm_phase(PG8_LAS unsigned char* lds, const Gemm g, const Sched& S, const Epi& E) {
;     ...
;         if constexpr (ALIGN_EPI) { if (wr == 0) PG8_BAR; }
;         if constexpr (!Epi::AFTER_DRAIN) { E(acc, cur, wr, wc, fr, fq); S.done(cur); }
.LBB0_960:
	s_cmp_lg_u64 s[38:39], 0
	s_cbranch_scc1 .Lskew_7
	s_sleep 3

; #define PG8_BAR __builtin_amdgcn_s_barrier()
; template <class Epi, class Sched, bool ALIGN_EPI = false, bool SP2 = false>
; __device__ __forceinline__ void gemm_phase(PG8_LAS unsigned char* lds, const Gemm g, const Sched& S, const Epi& E) {
;     ...
;         if constexpr (ALIGN_EPI) { if (wr == 0) PG8_BAR; }
;         if constexpr (!Epi::AFTER_DRAIN) { E(acc, cur, wr, wc, fr, fq); S.done(cur); }
.LBB0_1596:
	s_cmp_lg_u64 s[28:29], 0
	s_cbranch_scc1 .Lskew_12
	s_sleep 3

; #define PG8_BAR __builtin_amdgcn_s_barrier()
; template <class Epi, class Sched, bool ALIGN_EPI = false, bool SP2 = false>
; __device__ __forceinline__ void gemm_phase(PG8_LAS unsigned char* lds, const Gemm g, const Sched& S, const Epi& E) {
;     ...
;         if constexpr (ALIGN_EPI) { if (wr == 0) PG8_BAR; }
;         if constexpr (!Epi::AFTER_DRAIN) { E(acc, cur, wr, wc, fr, fq); S.done(cur); }
.LBB0_1819:
	s_cmp_lg_u64 s[24:25], 0
	s_cbranch_scc1 .Lskew_14
	s_sleep 3
